# seams 2,3,6,7,8 as XCD-local barriers (single per-XCC counter, no L2 writeback) with fallback to the global barrier
# speedup vs baseline: 1.0332x; 1.0332x over previous
.LBB0_95:
	s_or_b64 exec, exec, s[4:5]
	s_waitcnt lgkmcnt(0)
	s_barrier
	s_mov_b64 s[4:5], exec
	v_readlane_b32 s6, v255, 1
	v_readlane_b32 s7, v255, 2
	s_and_b64 s[6:7], s[4:5], s[6:7]
	s_mov_b64 exec, s[6:7]
	s_cbranch_execz .LBB0_107
	s_and_b32 s3, s34, 7
	s_cmp_eq_u32 s3, 0
	s_cselect_b64 s[6:7], -1, 0
	s_cmp_lt_u32 s33, 8
	s_cselect_b64 s[8:9], -1, 0
	s_and_b64 s[6:7], s[6:7], s[8:9]
	s_andn2_b64 vcc, exec, s[6:7]
	v_mov_b32_e32 v0, s80
	s_cbranch_vccnz .LBB0_106
	v_mov_b32_e32 v1, 0xfc00000
	global_load_dword v0, v1, s[30:31] offset:1024 sc1
	s_ashr_i32 s3, s34, 31
	s_lshr_b32 s3, s3, 29
	s_add_i32 s3, s34, s3
	s_ashr_i32 s3, s3, 3
	s_waitcnt vmcnt(0)
	v_cmp_ne_u32_e32 vcc, s3, v0
	v_mov_b32_e32 v0, s80
	s_cbranch_vccnz .LBB0_106
	global_load_dword v0, v1, s[30:31] offset:1280 sc1
	s_waitcnt vmcnt(0)
	v_cmp_ne_u32_e32 vcc, s3, v0
	v_mov_b32_e32 v0, s80
	s_cbranch_vccnz .LBB0_106
	v_mov_b32_e32 v1, 0xfc00000
	global_load_dword v0, v1, s[30:31] offset:1536 sc1
	s_waitcnt vmcnt(0)
	v_cmp_ne_u32_e32 vcc, s3, v0
	v_mov_b32_e32 v0, s80
	s_cbranch_vccnz .LBB0_106
	global_load_dword v0, v1, s[30:31] offset:1792 sc1
	s_waitcnt vmcnt(0)
	v_cmp_ne_u32_e32 vcc, s3, v0
	v_mov_b32_e32 v0, s80
	s_cbranch_vccnz .LBB0_106
	v_mov_b32_e32 v1, 0xfc00000
	global_load_dword v0, v1, s[30:31] offset:2048 sc1
	s_waitcnt vmcnt(0)
	v_cmp_ne_u32_e32 vcc, s3, v0
	v_mov_b32_e32 v0, s80
	s_cbranch_vccnz .LBB0_106
	global_load_dword v0, v1, s[30:31] offset:2304 sc1
	s_waitcnt vmcnt(0)
	v_cmp_ne_u32_e32 vcc, s3, v0
	v_mov_b32_e32 v0, s80
	s_cbranch_vccnz .LBB0_106
	v_mov_b32_e32 v1, 0xfc00000
	global_load_dword v0, v1, s[30:31] offset:2560 sc1
	s_waitcnt vmcnt(0)
	v_cmp_ne_u32_e32 vcc, s3, v0
	v_mov_b32_e32 v0, s80
	s_cbranch_vccnz .LBB0_106
	global_load_dword v0, v1, s[30:31] offset:2816 sc1
	s_waitcnt vmcnt(0)
	v_cmp_ne_u32_e32 vcc, s3, v0
	v_mov_b32_e32 v0, s80
	s_cbranch_vccnz .LBB0_106
	s_add_i32 s3, 0, 0x20048
	v_mov_b32_e32 v0, s3
	ds_read_b32 v0, v0
	s_waitcnt lgkmcnt(0)
	v_lshlrev_b32_e32 v0, 3, v0
	v_or_b32_e32 v0, s33, v0
	v_mov_b32_e32 v1, 0x20050
	ds_write_b32 v1, v1

.LBB0_262:
	s_cmp_gt_i32 s69, 3
	s_cselect_b64 s[0:1], -1, 0
	s_and_b64 s[2:3], s[4:5], s[0:1]
	s_andn2_b64 vcc, exec, s[2:3]
	s_cbranch_vccnz .LBB0_316
	s_waitcnt vmcnt(0)
	s_waitcnt vmcnt(0) lgkmcnt(0)
	s_barrier
	s_mov_b64 s[4:5], exec
	v_readlane_b32 s2, v255, 1
	v_readlane_b32 s3, v255, 2
	s_and_b64 s[2:3], s[4:5], s[2:3]
	s_mov_b64 exec, s[2:3]
	s_cbranch_execz .LBB0_315
	v_mov_b32_e32 v0, 0x20040
	ds_read_b32 v2, v0
	ds_read_b32 v3, v0 offset:16
	v_mov_b32_e32 v1, s33
	v_lshlrev_b32_e32 v1, 7, v1
	v_add_u32_e32 v0, 0x3600, v1
	v_mov_b32_e32 v1, 1
	s_waitcnt lgkmcnt(0)
	v_cmp_eq_u32_e32 vcc, 0, v3
	s_cbranch_vccnz .Lxl_orig_2
	v_mul_u32_u24_e32 v2, 1, v2
	global_atomic_add v0, v1, s[92:93]
	buffer_inv sc1
	s_mov_b32 s2, 0x20000
.Lxl_poll_2:
	global_load_dword v4, v0, s[92:93] sc1
	s_waitcnt vmcnt(0)
	v_cmp_ge_u32_e32 vcc, v4, v2
	s_cbranch_vccnz .LBB0_315
	s_sleep 1
	s_sub_u32 s2, s2, 1
	s_cmp_lg_u32 s2, 0
	s_cbranch_scc1 .Lxl_poll_2
	s_branch .LBB0_315
.Lxl_orig_2:
	s_add_i32 s2, 0, 0x20040
	v_mov_b32_e32 v0, s2
	s_waitcnt vmcnt(0) expcnt(0) lgkmcnt(0)
	ds_read_b32 v2, v0
	s_add_i32 s2, 0, 0x20044
	v_mov_b32_e32 v0, s2
	ds_read_b32 v0, v0
	s_waitcnt lgkmcnt(1)
	v_cmp_ne_u32_e32 vcc, 0, v2
	s_cbranch_vccnz .LBB0_279
	s_add_u32 s6, s30, 0xfc00200
	s_addc_u32 s7, s31, 0
	s_add_u32 s8, s30, 0xfc00400
	s_addc_u32 s9, s31, 0
	s_add_u32 s12, s30, 0xfc00500
	s_addc_u32 s13, s31, 0
	s_add_u32 s16, s30, 0xfc00600
	s_addc_u32 s17, s31, 0
	s_add_u32 s18, s30, 0xfc00700
	s_addc_u32 s19, s31, 0
	s_add_u32 s20, s30, 0xfc00800
	s_addc_u32 s21, s31, 0
	s_add_u32 s24, s30, 0xfc00900
	s_addc_u32 s25, s31, 0
	s_add_u32 s26, s30, 0xfc00a00
	s_addc_u32 s27, s31, 0
	s_add_u32 s50, s30, 0xfc00b00
	s_addc_u32 s51, s31, 0
	s_add_u32 s56, s30, 0xfc00c00
	s_addc_u32 s57, s31, 0
	s_add_u32 s58, s30, 0xfc00d00
	s_addc_u32 s59, s31, 0
	s_add_u32 s60, s30, 0xfc00e00
	s_addc_u32 s61, s31, 0
	s_add_u32 s62, s30, 0xfc00f00
	s_addc_u32 s63, s31, 0
	s_add_u32 s64, s30, 0xfc01000
	s_addc_u32 s65, s31, 0
	s_add_u32 s66, s30, 0xfc01100
	s_addc_u32 s67, s31, 0
	s_add_u32 s76, s30, 0xfc01200
	v_readlane_b32 s2, v255, 0
	s_addc_u32 s77, s31, 0
	s_mul_i32 s2, s35, s2
	s_add_u32 s78, s30, 0xfc01300
	s_mov_b32 s22, s80
	s_mov_b64 s[14:15], s[92:93]
	s_mul_i32 s2, s2, s34
	s_addc_u32 s79, s31, 0
	s_mov_b32 s3, 1
	v_mov_b32_e32 v16, 0
	s_branch .LBB0_267

.LBB0_363:
	s_cmp_gt_i32 s69, 4
	s_cselect_b64 s[0:1], -1, 0
	s_and_b64 s[2:3], s[8:9], s[0:1]
	s_andn2_b64 vcc, exec, s[2:3]
	s_cbranch_vccnz .LBB0_417
	s_waitcnt vmcnt(0)
	s_waitcnt vmcnt(0) lgkmcnt(0)
	s_barrier
	s_mov_b64 s[4:5], exec
	v_readlane_b32 s2, v255, 1
	v_readlane_b32 s3, v255, 2
	s_and_b64 s[2:3], s[4:5], s[2:3]
	s_mov_b64 exec, s[2:3]
	s_cbranch_execz .LBB0_416
	v_mov_b32_e32 v0, 0x20040
	ds_read_b32 v2, v0
	ds_read_b32 v3, v0 offset:16
	v_mov_b32_e32 v1, s33
	v_lshlrev_b32_e32 v1, 7, v1
	v_add_u32_e32 v0, 0x3600, v1
	v_mov_b32_e32 v1, 1
	s_waitcnt lgkmcnt(0)
	v_cmp_eq_u32_e32 vcc, 0, v3
	s_cbranch_vccnz .Lxl_orig_3
	v_mul_u32_u24_e32 v2, 2, v2
	global_atomic_add v0, v1, s[92:93]
	buffer_inv sc1
	s_mov_b32 s2, 0x20000

.Lxl_orig_3:
	s_add_i32 s2, 0, 0x20040
	v_mov_b32_e32 v0, s2
	s_waitcnt vmcnt(0) expcnt(0) lgkmcnt(0)
	ds_read_b32 v2, v0
	s_add_i32 s2, 0, 0x20044
	v_mov_b32_e32 v0, s2
	ds_read_b32 v0, v0
	s_waitcnt lgkmcnt(1)
	v_cmp_ne_u32_e32 vcc, 0, v2
	s_cbranch_vccnz .LBB0_380
	s_add_u32 s6, s30, 0xfc00200
	s_addc_u32 s7, s31, 0
	s_add_u32 s8, s30, 0xfc00400
	s_addc_u32 s9, s31, 0
	s_add_u32 s12, s30, 0xfc00500
	s_addc_u32 s13, s31, 0
	s_add_u32 s18, s30, 0xfc00600
	s_addc_u32 s19, s31, 0
	s_add_u32 s20, s30, 0xfc00700
	s_addc_u32 s21, s31, 0
	s_add_u32 s24, s30, 0xfc00800
	s_addc_u32 s25, s31, 0
	s_add_u32 s26, s30, 0xfc00900
	s_addc_u32 s27, s31, 0
	s_add_u32 s42, s30, 0xfc00a00
	s_addc_u32 s43, s31, 0
	s_add_u32 s50, s30, 0xfc00b00
	s_addc_u32 s51, s31, 0
	s_add_u32 s52, s30, 0xfc00c00
	s_addc_u32 s53, s31, 0
	s_add_u32 s54, s30, 0xfc00d00
	s_addc_u32 s55, s31, 0
	s_add_u32 s56, s30, 0xfc00e00
	s_addc_u32 s57, s31, 0
	s_add_u32 s58, s30, 0xfc00f00
	s_addc_u32 s59, s31, 0
	s_add_u32 s60, s30, 0xfc01000
	s_addc_u32 s61, s31, 0
	s_add_u32 s62, s30, 0xfc01100
	s_addc_u32 s63, s31, 0
	s_add_u32 s64, s30, 0xfc01200
	v_readlane_b32 s2, v255, 0
	s_addc_u32 s65, s31, 0
	s_mul_i32 s2, s35, s2
	s_add_u32 s66, s30, 0xfc01300
	s_mul_i32 s2, s2, s34
	s_addc_u32 s67, s31, 0
	s_mov_b32 s3, 1
	v_mov_b32_e32 v16, 0
	s_branch .LBB0_368

.LBB0_1502:
	s_cmp_gt_i32 s69, 7
	s_cselect_b64 s[2:3], -1, 0
	s_and_b64 s[0:1], s[0:1], s[2:3]
	s_andn2_b64 vcc, exec, s[0:1]
	s_cbranch_vccnz .LBB0_1556
	s_waitcnt vmcnt(0)
	s_waitcnt vmcnt(0) lgkmcnt(0)
	s_barrier
	s_mov_b64 s[0:1], exec
	v_readlane_b32 s4, v255, 1
	v_readlane_b32 s5, v255, 2
	s_and_b64 s[4:5], s[0:1], s[4:5]
	s_mov_b64 exec, s[4:5]
	s_cbranch_execz .LBB0_1555
	v_mov_b32_e32 v0, 0x20040
	ds_read_b32 v2, v0
	ds_read_b32 v3, v0 offset:16
	v_mov_b32_e32 v1, s33
	v_lshlrev_b32_e32 v1, 7, v1
	v_add_u32_e32 v0, 0x3600, v1
	v_mov_b32_e32 v1, 1
	s_waitcnt lgkmcnt(0)
	v_cmp_eq_u32_e32 vcc, 0, v3
	s_cbranch_vccnz .Lxl_orig_6
	v_mul_u32_u24_e32 v2, 3, v2
	global_atomic_add v0, v1, s[92:93]
	buffer_inv sc1
	s_mov_b32 s4, 0x20000
.Lxl_poll_6:
	global_load_dword v4, v0, s[92:93] sc1
	s_waitcnt vmcnt(0)
	v_cmp_ge_u32_e32 vcc, v4, v2
	s_cbranch_vccnz .LBB0_1555
	s_sleep 1
	s_sub_u32 s4, s4, 1
	s_cmp_lg_u32 s4, 0
	s_cbranch_scc1 .Lxl_poll_6
	s_branch .LBB0_1555
.Lxl_orig_6:
	s_add_i32 s4, 0, 0x20040
	v_mov_b32_e32 v0, s4
	s_waitcnt vmcnt(0) expcnt(0) lgkmcnt(0)
	ds_read_b32 v2, v0
	s_add_i32 s4, 0, 0x20044
	v_mov_b32_e32 v0, s4
	ds_read_b32 v0, v0
	s_waitcnt lgkmcnt(1)
	v_cmp_ne_u32_e32 vcc, 0, v2
	s_cbranch_vccnz .LBB0_1519
	v_readlane_b32 s4, v255, 0
	s_mul_i32 s16, s35, s4
	s_add_u32 s4, s30, 0xfc00200
	s_addc_u32 s5, s31, 0
	s_add_u32 s6, s30, 0xfc00400
	s_addc_u32 s7, s31, 0
	s_add_u32 s8, s30, 0xfc00500
	s_addc_u32 s9, s31, 0
	s_add_u32 s12, s30, 0xfc00600
	s_addc_u32 s13, s31, 0
	s_add_u32 s14, s30, 0xfc00700
	s_addc_u32 s15, s31, 0
	s_add_u32 s18, s30, 0xfc00800
	s_addc_u32 s19, s31, 0
	s_add_u32 s20, s30, 0xfc00900
	s_addc_u32 s21, s31, 0
	s_add_u32 s24, s30, 0xfc00a00
	s_addc_u32 s25, s31, 0
	s_add_u32 s26, s30, 0xfc00b00
	s_addc_u32 s27, s31, 0
	s_add_u32 s42, s30, 0xfc00c00
	s_addc_u32 s43, s31, 0
	s_add_u32 s44, s30, 0xfc00d00
	s_addc_u32 s45, s31, 0
	s_add_u32 s46, s30, 0xfc00e00
	s_addc_u32 s47, s31, 0
	s_add_u32 s48, s30, 0xfc00f00
	s_addc_u32 s49, s31, 0
	s_add_u32 s50, s30, 0xfc01000
	s_addc_u32 s51, s31, 0
	s_add_u32 s52, s30, 0xfc01100
	s_addc_u32 s53, s31, 0
	s_add_u32 s54, s30, 0xfc01200
	s_addc_u32 s55, s31, 0
	s_add_u32 s56, s30, 0xfc01300
	s_mul_i32 s16, s16, s34
	s_addc_u32 s57, s31, 0
	s_mov_b32 s17, 1
	v_mov_b32_e32 v16, 0
	s_branch .LBB0_1507

.LBB0_1599:
	s_cmp_gt_i32 s69, 8
	s_cselect_b64 s[2:3], -1, 0
	s_and_b64 s[0:1], s[0:1], s[2:3]
	v_readlane_b32 s60, v255, 20
	s_andn2_b64 vcc, exec, s[0:1]
	v_readlane_b32 s61, v255, 21
	s_cbranch_vccnz .LBB0_1653
	s_waitcnt vmcnt(0)
	s_waitcnt vmcnt(0) lgkmcnt(0)
	s_barrier
	s_mov_b64 s[0:1], exec
	v_readlane_b32 s4, v255, 1
	v_readlane_b32 s5, v255, 2
	s_and_b64 s[4:5], s[0:1], s[4:5]
	s_mov_b64 exec, s[4:5]
	s_cbranch_execz .LBB0_1652
	v_mov_b32_e32 v0, 0x20040
	ds_read_b32 v2, v0
	ds_read_b32 v3, v0 offset:16
	v_mov_b32_e32 v1, s33
	v_lshlrev_b32_e32 v1, 7, v1
	v_add_u32_e32 v0, 0x3600, v1
	v_mov_b32_e32 v1, 1
	s_waitcnt lgkmcnt(0)
	v_cmp_eq_u32_e32 vcc, 0, v3
	s_cbranch_vccnz .Lxl_orig_7
	v_mul_u32_u24_e32 v2, 4, v2
	global_atomic_add v0, v1, s[92:93]
	buffer_inv sc1
	s_mov_b32 s4, 0x20000

.Lxl_orig_7:
	s_add_i32 s4, 0, 0x20040
	v_mov_b32_e32 v0, s4
	s_waitcnt vmcnt(0) expcnt(0) lgkmcnt(0)
	ds_read_b32 v2, v0
	s_add_i32 s4, 0, 0x20044
	v_mov_b32_e32 v0, s4
	ds_read_b32 v0, v0
	s_waitcnt lgkmcnt(1)
	v_cmp_ne_u32_e32 vcc, 0, v2
	s_cbranch_vccnz .LBB0_1616
	v_readlane_b32 s4, v255, 0
	s_mul_i32 s16, s35, s4
	s_add_u32 s4, s30, 0xfc00200
	s_addc_u32 s5, s31, 0
	s_add_u32 s6, s30, 0xfc00400
	s_addc_u32 s7, s31, 0
	s_add_u32 s8, s30, 0xfc00500
	s_addc_u32 s9, s31, 0
	s_add_u32 s12, s30, 0xfc00600
	s_addc_u32 s13, s31, 0
	s_add_u32 s14, s30, 0xfc00700
	s_addc_u32 s15, s31, 0
	s_add_u32 s18, s30, 0xfc00800
	s_addc_u32 s19, s31, 0
	s_add_u32 s20, s30, 0xfc00900
	s_addc_u32 s21, s31, 0
	s_add_u32 s22, s30, 0xfc00a00
	s_addc_u32 s23, s31, 0
	s_add_u32 s24, s30, 0xfc00b00
	s_addc_u32 s25, s31, 0
	s_add_u32 s26, s30, 0xfc00c00
	s_addc_u32 s27, s31, 0
	s_add_u32 s42, s30, 0xfc00d00
	s_addc_u32 s43, s31, 0
	s_add_u32 s44, s30, 0xfc00e00
	s_addc_u32 s45, s31, 0
	s_add_u32 s46, s30, 0xfc00f00
	s_addc_u32 s47, s31, 0
	s_add_u32 s48, s30, 0xfc01000
	s_addc_u32 s49, s31, 0
	s_add_u32 s50, s30, 0xfc01100
	s_addc_u32 s51, s31, 0
	s_add_u32 s52, s30, 0xfc01200
	s_addc_u32 s53, s31, 0
	s_add_u32 s54, s30, 0xfc01300
	s_mul_i32 s16, s16, s34
	s_addc_u32 s55, s31, 0
	s_mov_b32 s17, 1
	v_mov_b32_e32 v16, 0
	s_branch .LBB0_1604

.LBB0_1710:
	s_cmp_gt_i32 s69, 9
	s_cselect_b64 s[0:1], -1, 0
	s_and_b64 s[2:3], s[6:7], s[0:1]
	s_andn2_b64 vcc, exec, s[2:3]
	s_cbranch_vccnz .LBB0_1764
	s_waitcnt vmcnt(0)
	s_waitcnt vmcnt(0) lgkmcnt(0)
	s_barrier
	s_mov_b64 s[2:3], exec
	v_readlane_b32 s4, v255, 1
	v_readlane_b32 s5, v255, 2
	s_and_b64 s[4:5], s[2:3], s[4:5]
	s_mov_b64 exec, s[4:5]
	s_cbranch_execz .LBB0_1763
	v_mov_b32_e32 v0, 0x20040
	ds_read_b32 v2, v0
	ds_read_b32 v3, v0 offset:16
	v_mov_b32_e32 v1, s33
	v_lshlrev_b32_e32 v1, 7, v1
	v_add_u32_e32 v0, 0x3600, v1
	v_mov_b32_e32 v1, 1
	s_waitcnt lgkmcnt(0)
	v_cmp_eq_u32_e32 vcc, 0, v3
	s_cbranch_vccnz .Lxl_orig_8
	v_mul_u32_u24_e32 v2, 5, v2
	global_atomic_add v0, v1, s[92:93]
	buffer_inv sc1
	s_mov_b32 s4, 0x20000

.Lxl_orig_8:
	s_add_i32 s4, 0, 0x20040
	v_mov_b32_e32 v0, s4
	s_waitcnt vmcnt(0) expcnt(0) lgkmcnt(0)
	ds_read_b32 v2, v0
	s_add_i32 s4, 0, 0x20044
	v_mov_b32_e32 v0, s4
	ds_read_b32 v0, v0
	s_waitcnt lgkmcnt(1)
	v_cmp_ne_u32_e32 vcc, 0, v2
	s_cbranch_vccnz .LBB0_1727
	v_readlane_b32 s4, v255, 0
	s_mul_i32 s35, s35, s4
	s_add_u32 s4, s30, 0xfc00200
	s_addc_u32 s5, s31, 0
	s_add_u32 s6, s30, 0xfc00400
	s_addc_u32 s7, s31, 0
	s_add_u32 s8, s30, 0xfc00500
	s_addc_u32 s9, s31, 0
	s_add_u32 s10, s30, 0xfc00600
	s_addc_u32 s11, s31, 0
	s_add_u32 s12, s30, 0xfc00700
	s_addc_u32 s13, s31, 0
	s_add_u32 s14, s30, 0xfc00800
	s_addc_u32 s15, s31, 0
	s_add_u32 s16, s30, 0xfc00900
	s_addc_u32 s17, s31, 0
	s_add_u32 s18, s30, 0xfc00a00
	s_addc_u32 s19, s31, 0
	s_add_u32 s20, s30, 0xfc00b00
	s_addc_u32 s21, s31, 0
	s_add_u32 s22, s30, 0xfc00c00
	s_addc_u32 s23, s31, 0
	s_add_u32 s24, s30, 0xfc00d00
	s_addc_u32 s25, s31, 0
	s_add_u32 s26, s30, 0xfc00e00
	s_addc_u32 s27, s31, 0
	s_add_u32 s40, s30, 0xfc00f00
	s_addc_u32 s41, s31, 0
	s_add_u32 s42, s30, 0xfc01000
	s_addc_u32 s43, s31, 0
	s_add_u32 s44, s30, 0xfc01100
	s_addc_u32 s45, s31, 0
	s_add_u32 s46, s30, 0xfc01200
	s_addc_u32 s47, s31, 0
	s_add_u32 s48, s30, 0xfc01300
	s_mul_i32 s35, s35, s34
	s_addc_u32 s49, s31, 0
	s_mov_b32 s39, 1
	v_mov_b32_e32 v16, 0
	s_branch .LBB0_1715
